# out-projection residual epilogue: the four x loads of each of the 8 row steps issued together with counted waits (was 32 serialized load/vmcnt(0)/store steps per unit)
# baseline (speedup 1.0000x reference)
; __device__ __forceinline__ unsigned cvt_pk_bf16(float lo, float hi) { unsigned r; asm volatile("v_cvt_pk_bf16_f32 %0, %1, %2" : "=v"(r) : "v"(lo), "v"(hi)); return r; }
;     __device__ __forceinline__ void operator()(const f32x4 (&acc)[2][2][4][2], const Unit& u, int wr, int wc, int fr, int fq) const {
;     ...
;         for (int ai = 0; ai < 2; ++ai)
; #pragma unroll
;             for (int m = 0; m < 4; ++m) {
;                 const int row = u.pm * BM + ai * HALF + wr * 64 + m * 16 + fr;
;                 const float* xin = row < split ? xa + (size_t)row * DM : xb + (size_t)(row - split) * DM;
;                 float q = 0.f;
; #pragma unroll
;                 for (int bj = 0; bj < 2; ++bj)
; #pragma unroll
;                     for (int n = 0; n < 2; ++n) {
;                         const int col = u.pn * BM + 128 * bj + 32 * wc + 16 * n + 4 * fq;
;                         const f32x4 v = acc[ai][bj][m][n] + *(const f32x4*)(xin + col);
;                         *(f32x4*)(o + (size_t)row * DM + col) = v;
;                         if (WB) *(u32x2*)(ob + (size_t)row * DM + col) = (u32x2){cvt_pk_bf16(v[0], v[1]), cvt_pk_bf16(v[2], v[3])};
;                         q += (v[0] * v[0] + v[1] * v[1]) + (v[2] * v[2] + v[3] * v[3]);
;                     }
;                 q += __shfl_xor(q, 16); q += __shfl_xor(q, 32);
;                 if (fq == 0) ss[(size_t)row * 16 + u.pn * 4 + wc] = q;
.LBB0_621:
	s_or_b64 exec, exec, s[30:31]
	v_lshl_or_b32 v146, s0, 8, v154
	v_ashrrev_i32_e32 v147, 31, v146
	v_lshlrev_b64 v[148:149], 2, v[146:147]
	v_lshl_add_u64 v[152:153], v[152:153], 0, v[148:149]
	global_load_dwordx4 v[158:161], v[152:153], off
	global_load_dwordx4 v[166:169], v[152:153], off offset:64
	global_load_dwordx4 v[170:173], v[152:153], off offset:512
	global_load_dwordx4 v[174:177], v[152:153], off offset:576
	v_readlane_b32 s36, v250, 0
	v_lshlrev_b64 v[162:163], 12, v[150:151]
	v_lshlrev_b64 v[164:165], 11, v[150:151]
	v_readlane_b32 s42, v250, 6
	v_readlane_b32 s43, v250, 7
	v_lshl_add_u64 v[164:165], s[8:9], 0, v[164:165]
	v_lshl_add_u64 v[164:165], v[146:147], 1, v[164:165]
	v_lshl_add_u64 v[162:163], s[42:43], 0, v[162:163]
	v_lshl_add_u64 v[162:163], v[162:163], 0, v[148:149]
	s_lshl_b32 s30, s0, 2
	s_ashr_i32 s31, s30, 31
	v_readlane_b32 s37, v250, 1
	v_readlane_b32 s38, v250, 2
	v_readlane_b32 s39, v250, 3
	v_readlane_b32 s40, v250, 4
	v_readlane_b32 s41, v250, 5
	s_waitcnt vmcnt(3)
	v_pk_add_f32 v[126:127], v[126:127], v[160:161]
	v_pk_add_f32 v[124:125], v[124:125], v[158:159]
	global_store_dwordx4 v[162:163], v[124:127], off
	v_cvt_pk_bf16_f32 v158, v124, v125
	v_cvt_pk_bf16_f32 v159, v126, v127
	global_store_dwordx2 v[164:165], v[158:159], off
	v_mul_f32_e32 v125, v125, v125
	v_mul_f32_e32 v127, v127, v127
	v_fmac_f32_e32 v125, v124, v124
	v_fmac_f32_e32 v127, v126, v126
	v_add_f32_e32 v124, v125, v127
	s_waitcnt vmcnt(4)
	v_pk_add_f32 v[122:123], v[122:123], v[168:169]
	v_pk_add_f32 v[120:121], v[120:121], v[166:167]
	global_store_dwordx4 v[162:163], v[120:123], off offset:64
	v_cvt_pk_bf16_f32 v158, v120, v121
	v_cvt_pk_bf16_f32 v159, v122, v123
	global_store_dwordx2 v[164:165], v[158:159], off offset:32
	v_mul_f32_e32 v121, v121, v121
	v_mul_f32_e32 v123, v123, v123
	v_fmac_f32_e32 v121, v120, v120
	v_fmac_f32_e32 v123, v122, v122
	v_add_f32_e32 v120, v121, v123
	v_add_f32_e32 v120, v124, v120
	s_waitcnt vmcnt(5)
	v_pk_add_f32 v[118:119], v[118:119], v[172:173]
	v_pk_add_f32 v[116:117], v[116:117], v[170:171]
	global_store_dwordx4 v[162:163], v[116:119], off offset:512
	v_cvt_pk_bf16_f32 v158, v116, v117
	v_cvt_pk_bf16_f32 v159, v118, v119
	global_store_dwordx2 v[164:165], v[158:159], off offset:256
	v_mul_f32_e32 v117, v117, v117
	v_mul_f32_e32 v119, v119, v119
	v_fmac_f32_e32 v117, v116, v116
	v_fmac_f32_e32 v119, v118, v118
	v_add_f32_e32 v116, v117, v119
	v_add_f32_e32 v118, v120, v116
	s_waitcnt vmcnt(6)
	v_pk_add_f32 v[116:117], v[114:115], v[176:177]
	v_pk_add_f32 v[114:115], v[112:113], v[174:175]
	v_mul_f32_e32 v113, v117, v117
	v_mul_f32_e32 v112, v115, v115
	v_fmac_f32_e32 v112, v114, v114
	v_fmac_f32_e32 v113, v116, v116
	v_add_f32_e32 v112, v112, v113
	v_add_f32_e32 v112, v118, v112
	ds_bpermute_b32 v113, v200, v112
	global_store_dwordx4 v[162:163], v[114:117], off offset:576
	s_waitcnt lgkmcnt(0)
	v_add_f32_e32 v112, v112, v113
	ds_bpermute_b32 v113, v201, v112
	v_cvt_pk_bf16_f32 v114, v114, v115
	v_cvt_pk_bf16_f32 v115, v116, v117
	global_store_dwordx2 v[164:165], v[114:115], off offset:288
	s_and_saveexec_b64 s[34:35], s[4:5]
	s_cbranch_execz .LBB0_623
	v_lshlrev_b64 v[114:115], 6, v[150:151]
	v_lshl_add_u64 v[114:115], s[10:11], 0, v[114:115]
	v_lshl_add_u64 v[114:115], s[30:31], 2, v[114:115]
	s_lshl_b32 s0, s48, 2
	v_lshl_add_u64 v[114:115], v[114:115], 0, s[0:1]
	s_waitcnt lgkmcnt(0)
	v_add_f32_e32 v112, v112, v113
	global_store_dword v[114:115], v112, off

; __device__ __forceinline__ unsigned cvt_pk_bf16(float lo, float hi) { unsigned r; asm volatile("v_cvt_pk_bf16_f32 %0, %1, %2" : "=v"(r) : "v"(lo), "v"(hi)); return r; }
;     __device__ __forceinline__ void operator()(const f32x4 (&acc)[2][2][4][2], const Unit& u, int wr, int wc, int fr, int fq) const {
;     ...
;         for (int ai = 0; ai < 2; ++ai)
; #pragma unroll
;             for (int m = 0; m < 4; ++m) {
;                 const int row = u.pm * BM + ai * HALF + wr * 64 + m * 16 + fr;
;                 const float* xin = row < split ? xa + (size_t)row * DM : xb + (size_t)(row - split) * DM;
;                 float q = 0.f;
; #pragma unroll
;                 for (int bj = 0; bj < 2; ++bj)
; #pragma unroll
;                     for (int n = 0; n < 2; ++n) {
;                         const int col = u.pn * BM + 128 * bj + 32 * wc + 16 * n + 4 * fq;
;                         const f32x4 v = acc[ai][bj][m][n] + *(const f32x4*)(xin + col);
;                         *(f32x4*)(o + (size_t)row * DM + col) = v;
;                         if (WB) *(u32x2*)(ob + (size_t)row * DM + col) = (u32x2){cvt_pk_bf16(v[0], v[1]), cvt_pk_bf16(v[2], v[3])};
;                         q += (v[0] * v[0] + v[1] * v[1]) + (v[2] * v[2] + v[3] * v[3]);
;                     }
;                 q += __shfl_xor(q, 16); q += __shfl_xor(q, 32);
;                 if (fq == 0) ss[(size_t)row * 16 + u.pn * 4 + wc] = q;
.LBB0_627:
	s_or_b64 exec, exec, s[34:35]
	v_lshl_add_u64 v[118:119], v[114:115], 0, v[148:149]
	global_load_dwordx4 v[114:117], v[118:119], off
	global_load_dwordx4 v[166:169], v[118:119], off offset:64
	global_load_dwordx4 v[170:173], v[118:119], off offset:512
	global_load_dwordx4 v[174:177], v[118:119], off offset:576
	v_readlane_b32 s36, v250, 0
	v_lshlrev_b64 v[120:121], 12, v[112:113]
	v_lshlrev_b64 v[122:123], 11, v[112:113]
	v_readlane_b32 s42, v250, 6
	v_readlane_b32 s43, v250, 7
	v_lshl_add_u64 v[122:123], s[8:9], 0, v[122:123]
	v_lshl_add_u64 v[122:123], v[146:147], 1, v[122:123]
	v_lshl_add_u64 v[120:121], s[42:43], 0, v[120:121]
	v_lshl_add_u64 v[120:121], v[120:121], 0, v[148:149]
	v_readlane_b32 s37, v250, 1
	v_readlane_b32 s38, v250, 2
	v_readlane_b32 s39, v250, 3
	v_readlane_b32 s40, v250, 4
	v_readlane_b32 s41, v250, 5
	s_waitcnt vmcnt(3)
	v_pk_add_f32 v[110:111], v[110:111], v[116:117]
	v_pk_add_f32 v[108:109], v[108:109], v[114:115]
	global_store_dwordx4 v[120:121], v[108:111], off
	v_cvt_pk_bf16_f32 v114, v108, v109
	v_cvt_pk_bf16_f32 v115, v110, v111
	global_store_dwordx2 v[122:123], v[114:115], off
	v_mul_f32_e32 v109, v109, v109
	v_mul_f32_e32 v111, v111, v111
	v_fmac_f32_e32 v109, v108, v108
	v_fmac_f32_e32 v111, v110, v110
	v_add_f32_e32 v108, v109, v111
	s_waitcnt vmcnt(4)
	v_pk_add_f32 v[106:107], v[106:107], v[168:169]
	v_pk_add_f32 v[104:105], v[104:105], v[166:167]
	global_store_dwordx4 v[120:121], v[104:107], off offset:64
	v_cvt_pk_bf16_f32 v114, v104, v105
	v_cvt_pk_bf16_f32 v115, v106, v107
	global_store_dwordx2 v[122:123], v[114:115], off offset:32
	v_mul_f32_e32 v105, v105, v105
	v_mul_f32_e32 v107, v107, v107
	v_fmac_f32_e32 v105, v104, v104
	v_fmac_f32_e32 v107, v106, v106
	v_add_f32_e32 v104, v105, v107
	v_add_f32_e32 v104, v108, v104
	s_waitcnt vmcnt(5)
	v_pk_add_f32 v[102:103], v[102:103], v[172:173]
	v_pk_add_f32 v[100:101], v[100:101], v[170:171]
	global_store_dwordx4 v[120:121], v[100:103], off offset:512
	v_cvt_pk_bf16_f32 v114, v100, v101
	v_cvt_pk_bf16_f32 v115, v102, v103
	global_store_dwordx2 v[122:123], v[114:115], off offset:256
	v_mul_f32_e32 v101, v101, v101
	v_mul_f32_e32 v103, v103, v103
	v_fmac_f32_e32 v101, v100, v100
	v_fmac_f32_e32 v103, v102, v102
	v_add_f32_e32 v100, v101, v103
	v_add_f32_e32 v102, v104, v100
	s_waitcnt vmcnt(6)
	v_pk_add_f32 v[100:101], v[98:99], v[176:177]
	v_pk_add_f32 v[98:99], v[96:97], v[174:175]
	v_mul_f32_e32 v97, v101, v101
	v_mul_f32_e32 v96, v99, v99
	v_fmac_f32_e32 v96, v98, v98
	v_fmac_f32_e32 v97, v100, v100
	v_add_f32_e32 v96, v96, v97
	v_add_f32_e32 v96, v102, v96
	ds_bpermute_b32 v97, v200, v96
	global_store_dwordx4 v[120:121], v[98:101], off offset:576
	s_waitcnt lgkmcnt(0)
	v_add_f32_e32 v96, v96, v97
	ds_bpermute_b32 v97, v201, v96
	v_cvt_pk_bf16_f32 v98, v98, v99
	v_cvt_pk_bf16_f32 v99, v100, v101
	global_store_dwordx2 v[122:123], v[98:99], off offset:288
	s_and_saveexec_b64 s[34:35], s[4:5]
	s_cbranch_execz .LBB0_629
	v_lshlrev_b64 v[98:99], 6, v[112:113]
	v_lshl_add_u64 v[98:99], s[10:11], 0, v[98:99]
	v_lshl_add_u64 v[98:99], s[30:31], 2, v[98:99]
	s_lshl_b32 s0, s48, 2
	v_lshl_add_u64 v[98:99], v[98:99], 0, s[0:1]
	s_waitcnt lgkmcnt(0)
	v_add_f32_e32 v96, v96, v97
	global_store_dword v[98:99], v96, off

; __device__ __forceinline__ unsigned cvt_pk_bf16(float lo, float hi) { unsigned r; asm volatile("v_cvt_pk_bf16_f32 %0, %1, %2" : "=v"(r) : "v"(lo), "v"(hi)); return r; }
;     __device__ __forceinline__ void operator()(const f32x4 (&acc)[2][2][4][2], const Unit& u, int wr, int wc, int fr, int fq) const {
;     ...
;         for (int ai = 0; ai < 2; ++ai)
; #pragma unroll
;             for (int m = 0; m < 4; ++m) {
;                 const int row = u.pm * BM + ai * HALF + wr * 64 + m * 16 + fr;
;                 const float* xin = row < split ? xa + (size_t)row * DM : xb + (size_t)(row - split) * DM;
;                 float q = 0.f;
; #pragma unroll
;                 for (int bj = 0; bj < 2; ++bj)
; #pragma unroll
;                     for (int n = 0; n < 2; ++n) {
;                         const int col = u.pn * BM + 128 * bj + 32 * wc + 16 * n + 4 * fq;
;                         const f32x4 v = acc[ai][bj][m][n] + *(const f32x4*)(xin + col);
;                         *(f32x4*)(o + (size_t)row * DM + col) = v;
;                         if (WB) *(u32x2*)(ob + (size_t)row * DM + col) = (u32x2){cvt_pk_bf16(v[0], v[1]), cvt_pk_bf16(v[2], v[3])};
;                         q += (v[0] * v[0] + v[1] * v[1]) + (v[2] * v[2] + v[3] * v[3]);
;                     }
;                 q += __shfl_xor(q, 16); q += __shfl_xor(q, 32);
;                 if (fq == 0) ss[(size_t)row * 16 + u.pn * 4 + wc] = q;
.LBB0_633:
	s_or_b64 exec, exec, s[34:35]
	v_lshl_add_u64 v[102:103], v[98:99], 0, v[148:149]
	global_load_dwordx4 v[98:101], v[102:103], off
	global_load_dwordx4 v[166:169], v[102:103], off offset:64
	global_load_dwordx4 v[170:173], v[102:103], off offset:512
	global_load_dwordx4 v[174:177], v[102:103], off offset:576
	v_readlane_b32 s36, v250, 0
	v_lshlrev_b64 v[104:105], 12, v[96:97]
	v_lshlrev_b64 v[106:107], 11, v[96:97]
	v_readlane_b32 s42, v250, 6
	v_readlane_b32 s43, v250, 7
	v_lshl_add_u64 v[106:107], s[8:9], 0, v[106:107]
	v_lshl_add_u64 v[106:107], v[146:147], 1, v[106:107]
	v_lshl_add_u64 v[104:105], s[42:43], 0, v[104:105]
	v_lshl_add_u64 v[104:105], v[104:105], 0, v[148:149]
	v_readlane_b32 s37, v250, 1
	v_readlane_b32 s38, v250, 2
	v_readlane_b32 s39, v250, 3
	v_readlane_b32 s40, v250, 4
	v_readlane_b32 s41, v250, 5
	s_waitcnt vmcnt(3)
	v_pk_add_f32 v[94:95], v[94:95], v[100:101]
	v_pk_add_f32 v[92:93], v[92:93], v[98:99]
	global_store_dwordx4 v[104:105], v[92:95], off
	v_cvt_pk_bf16_f32 v98, v92, v93
	v_cvt_pk_bf16_f32 v99, v94, v95
	global_store_dwordx2 v[106:107], v[98:99], off
	v_mul_f32_e32 v93, v93, v93
	v_mul_f32_e32 v95, v95, v95
	v_fmac_f32_e32 v93, v92, v92
	v_fmac_f32_e32 v95, v94, v94
	v_add_f32_e32 v92, v93, v95
	s_waitcnt vmcnt(4)
	v_pk_add_f32 v[90:91], v[90:91], v[168:169]
	v_pk_add_f32 v[88:89], v[88:89], v[166:167]
	global_store_dwordx4 v[104:105], v[88:91], off offset:64
	v_cvt_pk_bf16_f32 v98, v88, v89
	v_cvt_pk_bf16_f32 v99, v90, v91
	global_store_dwordx2 v[106:107], v[98:99], off offset:32
	v_mul_f32_e32 v89, v89, v89
	v_mul_f32_e32 v91, v91, v91
	v_fmac_f32_e32 v89, v88, v88
	v_fmac_f32_e32 v91, v90, v90
	v_add_f32_e32 v88, v89, v91
	v_add_f32_e32 v88, v92, v88
	s_waitcnt vmcnt(5)
	v_pk_add_f32 v[86:87], v[86:87], v[172:173]
	v_pk_add_f32 v[84:85], v[84:85], v[170:171]
	global_store_dwordx4 v[104:105], v[84:87], off offset:512
	v_cvt_pk_bf16_f32 v98, v84, v85
	v_cvt_pk_bf16_f32 v99, v86, v87
	global_store_dwordx2 v[106:107], v[98:99], off offset:256
	v_mul_f32_e32 v85, v85, v85
	v_mul_f32_e32 v87, v87, v87
	v_fmac_f32_e32 v85, v84, v84
	v_fmac_f32_e32 v87, v86, v86
	v_add_f32_e32 v84, v85, v87
	v_add_f32_e32 v86, v88, v84
	s_waitcnt vmcnt(6)
	v_pk_add_f32 v[84:85], v[82:83], v[176:177]
	v_pk_add_f32 v[82:83], v[80:81], v[174:175]
	v_mul_f32_e32 v81, v85, v85
	v_mul_f32_e32 v80, v83, v83
	v_fmac_f32_e32 v80, v82, v82
	v_fmac_f32_e32 v81, v84, v84
	v_add_f32_e32 v80, v80, v81
	v_add_f32_e32 v80, v86, v80
	ds_bpermute_b32 v81, v200, v80
	global_store_dwordx4 v[104:105], v[82:85], off offset:576
	s_waitcnt lgkmcnt(0)
	v_add_f32_e32 v80, v80, v81
	ds_bpermute_b32 v81, v201, v80
	v_cvt_pk_bf16_f32 v82, v82, v83
	v_cvt_pk_bf16_f32 v83, v84, v85
	global_store_dwordx2 v[106:107], v[82:83], off offset:288
	s_and_saveexec_b64 s[34:35], s[4:5]
	s_cbranch_execz .LBB0_635
	v_lshlrev_b64 v[82:83], 6, v[96:97]
	v_lshl_add_u64 v[82:83], s[10:11], 0, v[82:83]
	v_lshl_add_u64 v[82:83], s[30:31], 2, v[82:83]
	s_lshl_b32 s0, s48, 2
	v_lshl_add_u64 v[82:83], v[82:83], 0, s[0:1]
	s_waitcnt lgkmcnt(0)
	v_add_f32_e32 v80, v80, v81
	global_store_dword v[82:83], v80, off

; __device__ __forceinline__ unsigned cvt_pk_bf16(float lo, float hi) { unsigned r; asm volatile("v_cvt_pk_bf16_f32 %0, %1, %2" : "=v"(r) : "v"(lo), "v"(hi)); return r; }
;     __device__ __forceinline__ void operator()(const f32x4 (&acc)[2][2][4][2], const Unit& u, int wr, int wc, int fr, int fq) const {
;     ...
;                 const int row = u.pm * BM + ai * HALF + wr * 64 + m * 16 + fr;
;                 const float* xin = row < split ? xa + (size_t)row * DM : xb + (size_t)(row - split) * DM;
;                 float q = 0.f;
; #pragma unroll
;                 for (int bj = 0; bj < 2; ++bj)
; #pragma unroll
;                     for (int n = 0; n < 2; ++n) {
;                         const int col = u.pn * BM + 128 * bj + 32 * wc + 16 * n + 4 * fq;
;                         const f32x4 v = acc[ai][bj][m][n] + *(const f32x4*)(xin + col);
;                         *(f32x4*)(o + (size_t)row * DM + col) = v;
;                         if (WB) *(u32x2*)(ob + (size_t)row * DM + col) = (u32x2){cvt_pk_bf16(v[0], v[1]), cvt_pk_bf16(v[2], v[3])};
;                         q += (v[0] * v[0] + v[1] * v[1]) + (v[2] * v[2] + v[3] * v[3]);
;                     }
;                 q += __shfl_xor(q, 16); q += __shfl_xor(q, 32);
;                 if (fq == 0) ss[(size_t)row * 16 + u.pn * 4 + wc] = q;
.LBB0_639:
	s_or_b64 exec, exec, s[34:35]
	v_lshl_add_u64 v[86:87], v[82:83], 0, v[148:149]
	global_load_dwordx4 v[82:85], v[86:87], off
	global_load_dwordx4 v[166:169], v[86:87], off offset:64
	global_load_dwordx4 v[170:173], v[86:87], off offset:512
	global_load_dwordx4 v[174:177], v[86:87], off offset:576
	v_readlane_b32 s36, v250, 0
	v_lshlrev_b64 v[88:89], 12, v[80:81]
	v_lshlrev_b64 v[90:91], 11, v[80:81]
	v_readlane_b32 s42, v250, 6
	v_readlane_b32 s43, v250, 7
	v_lshl_add_u64 v[90:91], s[8:9], 0, v[90:91]
	v_lshl_add_u64 v[90:91], v[146:147], 1, v[90:91]
	v_lshl_add_u64 v[88:89], s[42:43], 0, v[88:89]
	v_lshl_add_u64 v[88:89], v[88:89], 0, v[148:149]
	v_readlane_b32 s37, v250, 1
	v_readlane_b32 s38, v250, 2
	v_readlane_b32 s39, v250, 3
	v_readlane_b32 s40, v250, 4
	v_readlane_b32 s41, v250, 5
	s_waitcnt vmcnt(3)
	v_pk_add_f32 v[78:79], v[78:79], v[84:85]
	v_pk_add_f32 v[76:77], v[76:77], v[82:83]
	global_store_dwordx4 v[88:89], v[76:79], off
	v_cvt_pk_bf16_f32 v82, v76, v77
	v_cvt_pk_bf16_f32 v83, v78, v79
	global_store_dwordx2 v[90:91], v[82:83], off
	v_mul_f32_e32 v77, v77, v77
	v_mul_f32_e32 v79, v79, v79
	v_fmac_f32_e32 v77, v76, v76
	v_fmac_f32_e32 v79, v78, v78
	v_add_f32_e32 v76, v77, v79
	s_waitcnt vmcnt(4)
	v_pk_add_f32 v[74:75], v[74:75], v[168:169]
	v_pk_add_f32 v[72:73], v[72:73], v[166:167]
	global_store_dwordx4 v[88:89], v[72:75], off offset:64
	v_cvt_pk_bf16_f32 v82, v72, v73
	v_cvt_pk_bf16_f32 v83, v74, v75
	global_store_dwordx2 v[90:91], v[82:83], off offset:32
	v_mul_f32_e32 v73, v73, v73
	v_mul_f32_e32 v75, v75, v75
	v_fmac_f32_e32 v73, v72, v72
	v_fmac_f32_e32 v75, v74, v74
	v_add_f32_e32 v72, v73, v75
	v_add_f32_e32 v72, v76, v72
	s_waitcnt vmcnt(5)
	v_pk_add_f32 v[70:71], v[70:71], v[172:173]
	v_pk_add_f32 v[68:69], v[68:69], v[170:171]
	global_store_dwordx4 v[88:89], v[68:71], off offset:512
	v_cvt_pk_bf16_f32 v82, v68, v69
	v_cvt_pk_bf16_f32 v83, v70, v71
	global_store_dwordx2 v[90:91], v[82:83], off offset:256
	v_mul_f32_e32 v69, v69, v69
	v_mul_f32_e32 v71, v71, v71
	v_fmac_f32_e32 v69, v68, v68
	v_fmac_f32_e32 v71, v70, v70
	v_add_f32_e32 v68, v69, v71
	v_add_f32_e32 v70, v72, v68
	s_waitcnt vmcnt(6)
	v_pk_add_f32 v[68:69], v[66:67], v[176:177]
	v_pk_add_f32 v[66:67], v[64:65], v[174:175]
	v_mul_f32_e32 v65, v69, v69
	v_mul_f32_e32 v64, v67, v67
	v_fmac_f32_e32 v64, v66, v66
	v_fmac_f32_e32 v65, v68, v68
	v_add_f32_e32 v64, v64, v65
	v_add_f32_e32 v64, v70, v64
	ds_bpermute_b32 v65, v200, v64
	global_store_dwordx4 v[88:89], v[66:69], off offset:576
	s_waitcnt lgkmcnt(0)
	v_add_f32_e32 v64, v64, v65
	ds_bpermute_b32 v65, v201, v64
	v_cvt_pk_bf16_f32 v66, v66, v67
	v_cvt_pk_bf16_f32 v67, v68, v69
	global_store_dwordx2 v[90:91], v[66:67], off offset:288
	s_and_saveexec_b64 s[34:35], s[4:5]
	s_cbranch_execz .LBB0_641
	v_lshlrev_b64 v[66:67], 6, v[80:81]
	v_lshl_add_u64 v[66:67], s[10:11], 0, v[66:67]
	v_lshl_add_u64 v[66:67], s[30:31], 2, v[66:67]
	s_lshl_b32 s0, s48, 2
	v_lshl_add_u64 v[66:67], v[66:67], 0, s[0:1]
	s_waitcnt lgkmcnt(0)
	v_add_f32_e32 v64, v64, v65
	global_store_dword v[66:67], v64, off

; __device__ __forceinline__ unsigned cvt_pk_bf16(float lo, float hi) { unsigned r; asm volatile("v_cvt_pk_bf16_f32 %0, %1, %2" : "=v"(r) : "v"(lo), "v"(hi)); return r; }
;     __device__ __forceinline__ void operator()(const f32x4 (&acc)[2][2][4][2], const Unit& u, int wr, int wc, int fr, int fq) const {
;     ...
;                 const int row = u.pm * BM + ai * HALF + wr * 64 + m * 16 + fr;
;                 const float* xin = row < split ? xa + (size_t)row * DM : xb + (size_t)(row - split) * DM;
;                 float q = 0.f;
; #pragma unroll
;                 for (int bj = 0; bj < 2; ++bj)
; #pragma unroll
;                     for (int n = 0; n < 2; ++n) {
;                         const int col = u.pn * BM + 128 * bj + 32 * wc + 16 * n + 4 * fq;
;                         const f32x4 v = acc[ai][bj][m][n] + *(const f32x4*)(xin + col);
;                         *(f32x4*)(o + (size_t)row * DM + col) = v;
;                         if (WB) *(u32x2*)(ob + (size_t)row * DM + col) = (u32x2){cvt_pk_bf16(v[0], v[1]), cvt_pk_bf16(v[2], v[3])};
;                         q += (v[0] * v[0] + v[1] * v[1]) + (v[2] * v[2] + v[3] * v[3]);
;                     }
;                 q += __shfl_xor(q, 16); q += __shfl_xor(q, 32);
;                 if (fq == 0) ss[(size_t)row * 16 + u.pn * 4 + wc] = q;
.LBB0_645:
	s_or_b64 exec, exec, s[34:35]
	v_lshl_add_u64 v[70:71], v[66:67], 0, v[148:149]
	global_load_dwordx4 v[66:69], v[70:71], off
	global_load_dwordx4 v[166:169], v[70:71], off offset:64
	global_load_dwordx4 v[170:173], v[70:71], off offset:512
	global_load_dwordx4 v[174:177], v[70:71], off offset:576
	v_readlane_b32 s36, v250, 0
	v_lshlrev_b64 v[72:73], 12, v[64:65]
	v_lshlrev_b64 v[74:75], 11, v[64:65]
	v_readlane_b32 s42, v250, 6
	v_readlane_b32 s43, v250, 7
	v_lshl_add_u64 v[74:75], s[8:9], 0, v[74:75]
	v_lshl_add_u64 v[74:75], v[146:147], 1, v[74:75]
	v_lshl_add_u64 v[72:73], s[42:43], 0, v[72:73]
	v_lshl_add_u64 v[72:73], v[72:73], 0, v[148:149]
	v_readlane_b32 s37, v250, 1
	v_readlane_b32 s38, v250, 2
	v_readlane_b32 s39, v250, 3
	v_readlane_b32 s40, v250, 4
	v_readlane_b32 s41, v250, 5
	s_waitcnt vmcnt(3)
	v_pk_add_f32 v[62:63], v[62:63], v[68:69]
	v_pk_add_f32 v[60:61], v[60:61], v[66:67]
	global_store_dwordx4 v[72:73], v[60:63], off
	v_cvt_pk_bf16_f32 v66, v60, v61
	v_cvt_pk_bf16_f32 v67, v62, v63
	global_store_dwordx2 v[74:75], v[66:67], off
	v_mul_f32_e32 v61, v61, v61
	v_mul_f32_e32 v63, v63, v63
	v_fmac_f32_e32 v61, v60, v60
	v_fmac_f32_e32 v63, v62, v62
	v_add_f32_e32 v60, v61, v63
	s_waitcnt vmcnt(4)
	v_pk_add_f32 v[58:59], v[58:59], v[168:169]
	v_pk_add_f32 v[56:57], v[56:57], v[166:167]
	global_store_dwordx4 v[72:73], v[56:59], off offset:64
	v_cvt_pk_bf16_f32 v66, v56, v57
	v_cvt_pk_bf16_f32 v67, v58, v59
	global_store_dwordx2 v[74:75], v[66:67], off offset:32
	v_mul_f32_e32 v57, v57, v57
	v_mul_f32_e32 v59, v59, v59
	v_fmac_f32_e32 v57, v56, v56
	v_fmac_f32_e32 v59, v58, v58
	v_add_f32_e32 v56, v57, v59
	v_add_f32_e32 v56, v60, v56
	s_waitcnt vmcnt(5)
	v_pk_add_f32 v[54:55], v[54:55], v[172:173]
	v_pk_add_f32 v[52:53], v[52:53], v[170:171]
	global_store_dwordx4 v[72:73], v[52:55], off offset:512
	v_cvt_pk_bf16_f32 v66, v52, v53
	v_cvt_pk_bf16_f32 v67, v54, v55
	global_store_dwordx2 v[74:75], v[66:67], off offset:256
	v_mul_f32_e32 v53, v53, v53
	v_mul_f32_e32 v55, v55, v55
	v_fmac_f32_e32 v53, v52, v52
	v_fmac_f32_e32 v55, v54, v54
	v_add_f32_e32 v52, v53, v55
	v_add_f32_e32 v54, v56, v52
	s_waitcnt vmcnt(6)
	v_pk_add_f32 v[52:53], v[50:51], v[176:177]
	v_pk_add_f32 v[50:51], v[48:49], v[174:175]
	v_mul_f32_e32 v49, v53, v53
	v_mul_f32_e32 v48, v51, v51
	v_fmac_f32_e32 v48, v50, v50
	v_fmac_f32_e32 v49, v52, v52
	v_add_f32_e32 v48, v48, v49
	v_add_f32_e32 v48, v54, v48
	ds_bpermute_b32 v49, v200, v48
	global_store_dwordx4 v[72:73], v[50:53], off offset:576
	s_waitcnt lgkmcnt(0)
	v_add_f32_e32 v48, v48, v49
	ds_bpermute_b32 v49, v201, v48
	v_cvt_pk_bf16_f32 v50, v50, v51
	v_cvt_pk_bf16_f32 v51, v52, v53
	global_store_dwordx2 v[74:75], v[50:51], off offset:288
	s_and_saveexec_b64 s[34:35], s[4:5]
	s_cbranch_execz .LBB0_647
	v_lshlrev_b64 v[50:51], 6, v[64:65]
	v_lshl_add_u64 v[50:51], s[10:11], 0, v[50:51]
	v_lshl_add_u64 v[50:51], s[30:31], 2, v[50:51]
	s_lshl_b32 s0, s48, 2
	v_lshl_add_u64 v[50:51], v[50:51], 0, s[0:1]
	s_waitcnt lgkmcnt(0)
	v_add_f32_e32 v48, v48, v49
	global_store_dword v[50:51], v48, off

; __device__ __forceinline__ unsigned cvt_pk_bf16(float lo, float hi) { unsigned r; asm volatile("v_cvt_pk_bf16_f32 %0, %1, %2" : "=v"(r) : "v"(lo), "v"(hi)); return r; }
;     __device__ __forceinline__ void operator()(const f32x4 (&acc)[2][2][4][2], const Unit& u, int wr, int wc, int fr, int fq) const {
;     ...
;                 const int row = u.pm * BM + ai * HALF + wr * 64 + m * 16 + fr;
;                 const float* xin = row < split ? xa + (size_t)row * DM : xb + (size_t)(row - split) * DM;
;                 float q = 0.f;
; #pragma unroll
;                 for (int bj = 0; bj < 2; ++bj)
; #pragma unroll
;                     for (int n = 0; n < 2; ++n) {
;                         const int col = u.pn * BM + 128 * bj + 32 * wc + 16 * n + 4 * fq;
;                         const f32x4 v = acc[ai][bj][m][n] + *(const f32x4*)(xin + col);
;                         *(f32x4*)(o + (size_t)row * DM + col) = v;
;                         if (WB) *(u32x2*)(ob + (size_t)row * DM + col) = (u32x2){cvt_pk_bf16(v[0], v[1]), cvt_pk_bf16(v[2], v[3])};
;                         q += (v[0] * v[0] + v[1] * v[1]) + (v[2] * v[2] + v[3] * v[3]);
;                     }
;                 q += __shfl_xor(q, 16); q += __shfl_xor(q, 32);
;                 if (fq == 0) ss[(size_t)row * 16 + u.pn * 4 + wc] = q;
.LBB0_651:
	s_or_b64 exec, exec, s[34:35]
	v_lshl_add_u64 v[54:55], v[50:51], 0, v[148:149]
	global_load_dwordx4 v[50:53], v[54:55], off
	global_load_dwordx4 v[166:169], v[54:55], off offset:64
	global_load_dwordx4 v[170:173], v[54:55], off offset:512
	global_load_dwordx4 v[174:177], v[54:55], off offset:576
	v_readlane_b32 s36, v250, 0
	v_lshlrev_b64 v[56:57], 12, v[48:49]
	v_lshlrev_b64 v[58:59], 11, v[48:49]
	v_readlane_b32 s42, v250, 6
	v_readlane_b32 s43, v250, 7
	v_lshl_add_u64 v[58:59], s[8:9], 0, v[58:59]
	v_lshl_add_u64 v[58:59], v[146:147], 1, v[58:59]
	v_lshl_add_u64 v[56:57], s[42:43], 0, v[56:57]
	v_lshl_add_u64 v[56:57], v[56:57], 0, v[148:149]
	v_readlane_b32 s37, v250, 1
	v_readlane_b32 s38, v250, 2
	v_readlane_b32 s39, v250, 3
	v_readlane_b32 s40, v250, 4
	v_readlane_b32 s41, v250, 5
	s_waitcnt vmcnt(3)
	v_pk_add_f32 v[46:47], v[46:47], v[52:53]
	v_pk_add_f32 v[44:45], v[44:45], v[50:51]
	global_store_dwordx4 v[56:57], v[44:47], off
	v_cvt_pk_bf16_f32 v50, v44, v45
	v_cvt_pk_bf16_f32 v51, v46, v47
	global_store_dwordx2 v[58:59], v[50:51], off
	v_mul_f32_e32 v45, v45, v45
	v_mul_f32_e32 v47, v47, v47
	v_fmac_f32_e32 v45, v44, v44
	v_fmac_f32_e32 v47, v46, v46
	v_add_f32_e32 v44, v45, v47
	s_waitcnt vmcnt(4)
	v_pk_add_f32 v[42:43], v[42:43], v[168:169]
	v_pk_add_f32 v[40:41], v[40:41], v[166:167]
	global_store_dwordx4 v[56:57], v[40:43], off offset:64
	v_cvt_pk_bf16_f32 v50, v40, v41
	v_cvt_pk_bf16_f32 v51, v42, v43
	global_store_dwordx2 v[58:59], v[50:51], off offset:32
	v_mul_f32_e32 v41, v41, v41
	v_mul_f32_e32 v43, v43, v43
	v_fmac_f32_e32 v41, v40, v40
	v_fmac_f32_e32 v43, v42, v42
	v_add_f32_e32 v40, v41, v43
	v_add_f32_e32 v40, v44, v40
	s_waitcnt vmcnt(5)
	v_pk_add_f32 v[38:39], v[38:39], v[172:173]
	v_pk_add_f32 v[36:37], v[36:37], v[170:171]
	global_store_dwordx4 v[56:57], v[36:39], off offset:512
	v_cvt_pk_bf16_f32 v50, v36, v37
	v_cvt_pk_bf16_f32 v51, v38, v39
	global_store_dwordx2 v[58:59], v[50:51], off offset:256
	v_mul_f32_e32 v37, v37, v37
	v_mul_f32_e32 v39, v39, v39
	v_fmac_f32_e32 v37, v36, v36
	v_fmac_f32_e32 v39, v38, v38
	v_add_f32_e32 v36, v37, v39
	v_add_f32_e32 v38, v40, v36
	s_waitcnt vmcnt(6)
	v_pk_add_f32 v[36:37], v[34:35], v[176:177]
	v_pk_add_f32 v[34:35], v[32:33], v[174:175]
	v_mul_f32_e32 v33, v37, v37
	v_mul_f32_e32 v32, v35, v35
	v_fmac_f32_e32 v32, v34, v34
	v_fmac_f32_e32 v33, v36, v36
	v_add_f32_e32 v32, v32, v33
	v_add_f32_e32 v32, v38, v32
	ds_bpermute_b32 v33, v200, v32
	global_store_dwordx4 v[56:57], v[34:37], off offset:576
	s_waitcnt lgkmcnt(0)
	v_add_f32_e32 v32, v32, v33
	ds_bpermute_b32 v33, v201, v32
	v_cvt_pk_bf16_f32 v34, v34, v35
	v_cvt_pk_bf16_f32 v35, v36, v37
	global_store_dwordx2 v[58:59], v[34:35], off offset:288
	s_and_saveexec_b64 s[34:35], s[4:5]
	s_cbranch_execz .LBB0_653
	v_lshlrev_b64 v[34:35], 6, v[48:49]
	v_lshl_add_u64 v[34:35], s[10:11], 0, v[34:35]
	v_lshl_add_u64 v[34:35], s[30:31], 2, v[34:35]
	s_lshl_b32 s0, s48, 2
	v_lshl_add_u64 v[34:35], v[34:35], 0, s[0:1]
	s_waitcnt lgkmcnt(0)
	v_add_f32_e32 v32, v32, v33
	global_store_dword v[34:35], v32, off

; __device__ __forceinline__ unsigned cvt_pk_bf16(float lo, float hi) { unsigned r; asm volatile("v_cvt_pk_bf16_f32 %0, %1, %2" : "=v"(r) : "v"(lo), "v"(hi)); return r; }
;     __device__ __forceinline__ void operator()(const f32x4 (&acc)[2][2][4][2], const Unit& u, int wr, int wc, int fr, int fq) const {
;     ...
;                 const int row = u.pm * BM + ai * HALF + wr * 64 + m * 16 + fr;
;                 const float* xin = row < split ? xa + (size_t)row * DM : xb + (size_t)(row - split) * DM;
;                 float q = 0.f;
; #pragma unroll
;                 for (int bj = 0; bj < 2; ++bj)
; #pragma unroll
;                     for (int n = 0; n < 2; ++n) {
;                         const int col = u.pn * BM + 128 * bj + 32 * wc + 16 * n + 4 * fq;
;                         const f32x4 v = acc[ai][bj][m][n] + *(const f32x4*)(xin + col);
;                         *(f32x4*)(o + (size_t)row * DM + col) = v;
;                         if (WB) *(u32x2*)(ob + (size_t)row * DM + col) = (u32x2){cvt_pk_bf16(v[0], v[1]), cvt_pk_bf16(v[2], v[3])};
;                         q += (v[0] * v[0] + v[1] * v[1]) + (v[2] * v[2] + v[3] * v[3]);
;                     }
;                 q += __shfl_xor(q, 16); q += __shfl_xor(q, 32);
;                 if (fq == 0) ss[(size_t)row * 16 + u.pn * 4 + wc] = q;
.LBB0_657:
	s_or_b64 exec, exec, s[34:35]
	v_lshl_add_u64 v[38:39], v[34:35], 0, v[148:149]
	global_load_dwordx4 v[34:37], v[38:39], off
	global_load_dwordx4 v[166:169], v[38:39], off offset:64
	global_load_dwordx4 v[170:173], v[38:39], off offset:512
	global_load_dwordx4 v[174:177], v[38:39], off offset:576
	v_readlane_b32 s36, v250, 0
	v_lshlrev_b64 v[40:41], 12, v[32:33]
	v_lshlrev_b64 v[42:43], 11, v[32:33]
	v_readlane_b32 s42, v250, 6
	v_readlane_b32 s43, v250, 7
	v_lshl_add_u64 v[42:43], s[8:9], 0, v[42:43]
	v_lshl_add_u64 v[42:43], v[146:147], 1, v[42:43]
	v_lshl_add_u64 v[40:41], s[42:43], 0, v[40:41]
	v_lshl_add_u64 v[40:41], v[40:41], 0, v[148:149]
	v_readlane_b32 s37, v250, 1
	v_readlane_b32 s38, v250, 2
	v_readlane_b32 s39, v250, 3
	v_readlane_b32 s40, v250, 4
	v_readlane_b32 s41, v250, 5
	s_waitcnt vmcnt(3)
	v_pk_add_f32 v[30:31], v[30:31], v[36:37]
	v_pk_add_f32 v[28:29], v[28:29], v[34:35]
	global_store_dwordx4 v[40:41], v[28:31], off
	v_cvt_pk_bf16_f32 v34, v28, v29
	v_cvt_pk_bf16_f32 v35, v30, v31
	global_store_dwordx2 v[42:43], v[34:35], off
	v_mul_f32_e32 v29, v29, v29
	v_mul_f32_e32 v31, v31, v31
	v_fmac_f32_e32 v29, v28, v28
	v_fmac_f32_e32 v31, v30, v30
	v_add_f32_e32 v28, v29, v31
	s_waitcnt vmcnt(4)
	v_pk_add_f32 v[26:27], v[26:27], v[168:169]
	v_pk_add_f32 v[24:25], v[24:25], v[166:167]
	global_store_dwordx4 v[40:41], v[24:27], off offset:64
	v_cvt_pk_bf16_f32 v34, v24, v25
	v_cvt_pk_bf16_f32 v35, v26, v27
	global_store_dwordx2 v[42:43], v[34:35], off offset:32
	v_mul_f32_e32 v25, v25, v25
	v_mul_f32_e32 v27, v27, v27
	v_fmac_f32_e32 v25, v24, v24
	v_fmac_f32_e32 v27, v26, v26
	v_add_f32_e32 v24, v25, v27
	v_add_f32_e32 v24, v28, v24
	s_waitcnt vmcnt(5)
	v_pk_add_f32 v[22:23], v[22:23], v[172:173]
	v_pk_add_f32 v[20:21], v[20:21], v[170:171]
	global_store_dwordx4 v[40:41], v[20:23], off offset:512
	v_cvt_pk_bf16_f32 v34, v20, v21
	v_cvt_pk_bf16_f32 v35, v22, v23
	global_store_dwordx2 v[42:43], v[34:35], off offset:256
	v_mul_f32_e32 v21, v21, v21
	v_mul_f32_e32 v23, v23, v23
	v_fmac_f32_e32 v21, v20, v20
	v_fmac_f32_e32 v23, v22, v22
	v_add_f32_e32 v20, v21, v23
	v_add_f32_e32 v22, v24, v20
	s_waitcnt vmcnt(6)
	v_pk_add_f32 v[20:21], v[18:19], v[176:177]
	v_pk_add_f32 v[18:19], v[16:17], v[174:175]
	v_mul_f32_e32 v17, v21, v21
	v_mul_f32_e32 v16, v19, v19
	v_fmac_f32_e32 v16, v18, v18
	v_fmac_f32_e32 v17, v20, v20
	v_add_f32_e32 v16, v16, v17
	v_add_f32_e32 v16, v22, v16
	ds_bpermute_b32 v17, v200, v16
	global_store_dwordx4 v[40:41], v[18:21], off offset:576
	s_waitcnt lgkmcnt(0)
	v_add_f32_e32 v16, v16, v17
	ds_bpermute_b32 v17, v201, v16
	v_cvt_pk_bf16_f32 v18, v18, v19
	v_cvt_pk_bf16_f32 v19, v20, v21
	global_store_dwordx2 v[42:43], v[18:19], off offset:288
	s_and_saveexec_b64 s[34:35], s[4:5]
	s_cbranch_execz .LBB0_659
	v_lshlrev_b64 v[18:19], 6, v[32:33]
	v_lshl_add_u64 v[18:19], s[10:11], 0, v[18:19]
	v_lshl_add_u64 v[18:19], s[30:31], 2, v[18:19]
	s_lshl_b32 s0, s48, 2
	v_lshl_add_u64 v[18:19], v[18:19], 0, s[0:1]
	s_waitcnt lgkmcnt(0)
	v_add_f32_e32 v16, v16, v17
	global_store_dword v[18:19], v16, off

; __device__ __forceinline__ unsigned cvt_pk_bf16(float lo, float hi) { unsigned r; asm volatile("v_cvt_pk_bf16_f32 %0, %1, %2" : "=v"(r) : "v"(lo), "v"(hi)); return r; }
;     __device__ __forceinline__ void operator()(const f32x4 (&acc)[2][2][4][2], const Unit& u, int wr, int wc, int fr, int fq) const {
;     ...
;                 const int row = u.pm * BM + ai * HALF + wr * 64 + m * 16 + fr;
;                 const float* xin = row < split ? xa + (size_t)row * DM : xb + (size_t)(row - split) * DM;
;                 float q = 0.f;
; #pragma unroll
;                 for (int bj = 0; bj < 2; ++bj)
; #pragma unroll
;                     for (int n = 0; n < 2; ++n) {
;                         const int col = u.pn * BM + 128 * bj + 32 * wc + 16 * n + 4 * fq;
;                         const f32x4 v = acc[ai][bj][m][n] + *(const f32x4*)(xin + col);
;                         *(f32x4*)(o + (size_t)row * DM + col) = v;
;                         if (WB) *(u32x2*)(ob + (size_t)row * DM + col) = (u32x2){cvt_pk_bf16(v[0], v[1]), cvt_pk_bf16(v[2], v[3])};
;                         q += (v[0] * v[0] + v[1] * v[1]) + (v[2] * v[2] + v[3] * v[3]);
;                     }
;                 q += __shfl_xor(q, 16); q += __shfl_xor(q, 32);
;                 if (fq == 0) ss[(size_t)row * 16 + u.pn * 4 + wc] = q;
.LBB0_663:
	s_or_b64 exec, exec, s[34:35]
	v_lshl_add_u64 v[22:23], v[18:19], 0, v[148:149]
	global_load_dwordx4 v[18:21], v[22:23], off
	global_load_dwordx4 v[166:169], v[22:23], off offset:64
	global_load_dwordx4 v[170:173], v[22:23], off offset:512
	global_load_dwordx4 v[174:177], v[22:23], off offset:576
	v_readlane_b32 s36, v250, 0
	v_lshlrev_b64 v[24:25], 12, v[16:17]
	v_lshlrev_b64 v[26:27], 11, v[16:17]
	v_readlane_b32 s42, v250, 6
	v_readlane_b32 s43, v250, 7
	v_lshl_add_u64 v[26:27], s[8:9], 0, v[26:27]
	v_lshl_add_u64 v[26:27], v[146:147], 1, v[26:27]
	v_lshl_add_u64 v[24:25], s[42:43], 0, v[24:25]
	v_lshl_add_u64 v[24:25], v[24:25], 0, v[148:149]
	v_readlane_b32 s37, v250, 1
	v_readlane_b32 s38, v250, 2
	v_readlane_b32 s39, v250, 3
	v_readlane_b32 s40, v250, 4
	v_readlane_b32 s41, v250, 5
	s_waitcnt vmcnt(3)
	v_pk_add_f32 v[14:15], v[14:15], v[20:21]
	v_pk_add_f32 v[12:13], v[12:13], v[18:19]
	global_store_dwordx4 v[24:25], v[12:15], off
	v_cvt_pk_bf16_f32 v18, v12, v13
	v_cvt_pk_bf16_f32 v19, v14, v15
	global_store_dwordx2 v[26:27], v[18:19], off
	v_mul_f32_e32 v13, v13, v13
	v_mul_f32_e32 v15, v15, v15
	v_fmac_f32_e32 v13, v12, v12
	v_fmac_f32_e32 v15, v14, v14
	v_add_f32_e32 v12, v13, v15
	s_waitcnt vmcnt(4)
	v_pk_add_f32 v[10:11], v[10:11], v[168:169]
	v_pk_add_f32 v[8:9], v[8:9], v[166:167]
	global_store_dwordx4 v[24:25], v[8:11], off offset:64
	v_cvt_pk_bf16_f32 v18, v8, v9
	v_cvt_pk_bf16_f32 v19, v10, v11
	global_store_dwordx2 v[26:27], v[18:19], off offset:32
	v_mul_f32_e32 v9, v9, v9
	v_mul_f32_e32 v11, v11, v11
	v_fmac_f32_e32 v9, v8, v8
	v_fmac_f32_e32 v11, v10, v10
	v_add_f32_e32 v8, v9, v11
	v_add_f32_e32 v8, v12, v8
	s_waitcnt vmcnt(5)
	v_pk_add_f32 v[6:7], v[6:7], v[172:173]
	v_pk_add_f32 v[4:5], v[4:5], v[170:171]
	global_store_dwordx4 v[24:25], v[4:7], off offset:512
	v_cvt_pk_bf16_f32 v18, v4, v5
	v_cvt_pk_bf16_f32 v19, v6, v7
	global_store_dwordx2 v[26:27], v[18:19], off offset:256
	v_mul_f32_e32 v5, v5, v5
	v_mul_f32_e32 v7, v7, v7
	v_fmac_f32_e32 v5, v4, v4
	v_fmac_f32_e32 v7, v6, v6
	v_add_f32_e32 v4, v5, v7
	v_add_f32_e32 v6, v8, v4
	s_waitcnt vmcnt(6)
	v_pk_add_f32 v[4:5], v[2:3], v[176:177]
	v_pk_add_f32 v[2:3], v[0:1], v[174:175]
	v_mul_f32_e32 v1, v5, v5
	v_mul_f32_e32 v0, v3, v3
	v_fmac_f32_e32 v0, v2, v2
	v_fmac_f32_e32 v1, v4, v4
	v_add_f32_e32 v0, v0, v1
	v_add_f32_e32 v0, v6, v0
	ds_bpermute_b32 v1, v200, v0
	global_store_dwordx4 v[24:25], v[2:5], off offset:576
	s_waitcnt lgkmcnt(0)
	v_add_f32_e32 v0, v0, v1
	ds_bpermute_b32 v1, v201, v0
	v_cvt_pk_bf16_f32 v2, v2, v3
	v_cvt_pk_bf16_f32 v3, v4, v5
	global_store_dwordx2 v[26:27], v[2:3], off offset:288
	s_and_saveexec_b64 s[34:35], s[4:5]
	s_cbranch_execz .LBB0_665
	v_lshlrev_b64 v[2:3], 6, v[16:17]
	v_lshl_add_u64 v[2:3], s[10:11], 0, v[2:3]
	v_lshl_add_u64 v[2:3], s[30:31], 2, v[2:3]
	s_lshl_b32 s0, s48, 2
	v_lshl_add_u64 v[2:3], v[2:3], 0, s[0:1]
	s_waitcnt lgkmcnt(0)
	v_add_f32_e32 v0, v0, v1
	global_store_dword v[2:3], v0, off
